# P4: x tile of the fused epilogue prefetched during the out-proj main loop (2 coalesced loads per wave per k-iteration)
# baseline (speedup 1.0000x reference)
; #define PG8_STAGE(bufoff, gbase, voff) do { _Pragma("unroll") for (int _i = 0; _i < 2; ++_i) \
;         __builtin_amdgcn_global_load_lds((const unsigned*)((const char*)(gbase) + (voff)[_i]), (LAS unsigned*)(lds + (bufoff) + ldsw + _i * 8192), 16, 0, 0); } while (0)
; #define PG8_LDA(dst, b, h) do { _Pragma("unroll") for (int m = 0; m < 4; ++m) _Pragma("unroll") for (int k = 0; k < 2; ++k) dst[m][k] = *(const LAS bf16x8*)(lds + PG8_SA(b, h) + aoff + m * 2048 + k * 1024); } while (0)
; #define PG8_LDB(dst, b, h) do { _Pragma("unroll") for (int n = 0; n < 2; ++n) _Pragma("unroll") for (int k = 0; k < 2; ++k) dst[n][k] = *(const LAS bf16x8*)(lds + PG8_SB(b, h) + boff + n * 2048 + k * 1024); } while (0)
; #define PG8_MMA(ai, bj, At, Bt) do { __builtin_amdgcn_s_setprio(1); _Pragma("unroll") for (int m = 0; m < 4; ++m) _Pragma("unroll") for (int n = 0; n < 2; ++n) _Pragma("unroll") for (int k = 0; k < 2; ++k) \
;         acc[ai][bj][m][n] = __builtin_amdgcn_mfma_f32_16x16x32_bf16(Bt[n][k], At[m][k], acc[ai][bj][m][n], 0, 0, 0); __builtin_amdgcn_s_setprio(0); } while (0)
; #define PG8_BAR __builtin_amdgcn_s_barrier()
; template <class Epi, class Sched>
; __device__ __forceinline__ void gemm_phase(LAS unsigned char* lds, const Gemm g, const Sched& S, const Epi& E) {
;     ...
;         const bool has_next = S.next(ui + 1, nxt);
;         const char* nA = has_next ? (const char*)g.A + (size_t)nxt.pm * tstepA : cA; const char* nB = has_next ? (const char*)g.Bt + (size_t)nxt.pn * tstepB : cB;
;         for (int t = 0; t < nt; t += 2) {
;             const bool last = (t == nt - 2);
;             const char* a1 = cA + (size_t)(t >> 1) * g.pairstep + kstep;
;             const char* a2 = last ? nA : cA + (size_t)((t >> 1) + 1) * g.pairstep; const char* b2 = last ? nB : cB + (size_t)(t + 2) * kstep;
;             const char* a3 = a2 + kstep; const char* b3 = b2 + kstep;
;             PG8_LDB(B0, 0, 0); PG8_SCHED; PG8_LDA(At, 0, 0); PG8_STAGE(PG8_SA(1, 1), a1 + hstepA, voffA);
;             PG8_WAIT_L(8); PG8_BAR; PG8_WAIT_L(0); PG8_MMA(0, 0, At, B0); PG8_BAR; PG8_SCHED;
;             PG8_LDB(B1, 0, 1); PG8_STAGE(PG8_SB(0, 0), b2, voffB);
;             PG8_BAR; PG8_WAIT_L(0); PG8_MMA(0, 1, At, B1); PG8_BAR;
;             PG8_LDA(At, 0, 1); PG8_STAGE(PG8_SA(0, 0), a2, voffA);
;             PG8_BAR; PG8_WAIT_L(0); PG8_MMA(1, 0, At, B0); PG8_BAR; PG8_SCHED;
.LBB0_429:
	s_ashr_i32 s43, s42, 31
	s_lshl_b64 s[46:47], s[42:43], 16
	s_add_u32 s46, s2, s46
	s_addc_u32 s47, s3, s47
	s_and_b64 s[48:49], s[4:5], exec
	s_cselect_b32 s43, s47, s21
	s_cselect_b32 s45, s46, s20
	s_ashr_i32 s41, s40, 31
	s_lshl_b64 s[48:49], s[40:41], 20
	s_add_u32 s48, s6, s48
	s_addc_u32 s49, s7, s49
	s_and_b64 s[50:51], s[4:5], exec
	s_cselect_b32 s41, s49, s19
	s_cselect_b32 s63, s48, s18
	s_add_u32 s64, s18, 0x100
	s_addc_u32 s65, s19, 0
	s_mov_b32 s66, -2
	s_mov_b64 s[50:51], 0x400000
	v_mov_b64_e32 v[144:145], v[138:139]
	v_mov_b64_e32 v[146:147], v[136:137]
	s_lshl_b32 s98, s14, 20
	s_lshl_b32 s99, s16, 10
	s_add_u32 s98, s98, s99
	s_add_u32 s98, s36, s98
	s_addc_u32 s99, s37, 0
	v_lshrrev_b32_e32 v232, 6, v167
	v_lshlrev_b32_e32 v232, 12, v232
	v_and_b32_e32 v233, 63, v167
	v_lshl_add_u32 v232, v233, 4, v232
	v_mov_b32_e32 v233, 0
	v_lshl_add_u64 v[232:233], s[98:99], 0, v[232:233]
	s_mov_b32 s98, 0x8000
	s_mov_b32 s99, 0
.LBB0_430:
	v_add_u32_e32 v153, s61, v149
	ds_read_b128 v[154:157], v153
	ds_read_b128 v[158:161], v153 offset:1024
	ds_read_b128 v[162:165], v153 offset:2048
	ds_read_b128 v[168:171], v153 offset:3072
	s_add_u32 s52, s20, s50
	s_addc_u32 s53, s21, s51
	s_cmp_eq_u32 s66, 28
	s_cselect_b32 s55, s43, s53
	s_cselect_b32 s54, s45, s52
	s_cselect_b32 s53, s41, s65
	s_cselect_b32 s52, s63, s64
	v_lshl_add_u64 v[204:205], s[20:21], 0, v[146:147]
	s_add_i32 m0, s28, 0xc000
	ds_read_b128 v[172:175], v151
	ds_read_b128 v[176:179], v151 offset:1024
	ds_read_b128 v[180:183], v151 offset:2048
	ds_read_b128 v[184:187], v151 offset:3072
	ds_read_b128 v[188:191], v151 offset:4096
	ds_read_b128 v[192:195], v151 offset:5120
	ds_read_b128 v[196:199], v151 offset:6144
	ds_read_b128 v[200:203], v151 offset:7168
	global_load_lds_dwordx4 v[204:205], off
	v_lshl_add_u64 v[204:205], s[20:21], 0, v[144:145]
	s_add_i32 m0, s28, 0xe000
	s_nop 0
	global_load_lds_dwordx4 v[204:205], off
	s_waitcnt lgkmcnt(8)
	s_barrier
	s_waitcnt lgkmcnt(0)
	s_setprio 1
	s_waitcnt lgkmcnt(0)
	v_mfma_f32_16x16x32_bf16 v[124:127], v[154:157], v[172:175], v[124:127]
	v_mfma_f32_16x16x32_bf16 v[120:123], v[162:165], v[172:175], v[120:123]
	v_mfma_f32_16x16x32_bf16 v[108:111], v[154:157], v[180:183], v[108:111]
	v_mfma_f32_16x16x32_bf16 v[104:107], v[162:165], v[180:183], v[104:107]
	v_mfma_f32_16x16x32_bf16 v[92:95], v[154:157], v[188:191], v[92:95]
	v_mfma_f32_16x16x32_bf16 v[88:91], v[162:165], v[188:191], v[88:91]
	v_mfma_f32_16x16x32_bf16 v[76:79], v[154:157], v[196:199], v[76:79]
	v_mfma_f32_16x16x32_bf16 v[72:75], v[162:165], v[196:199], v[72:75]
	v_mfma_f32_16x16x32_bf16 v[124:127], v[158:161], v[176:179], v[124:127]
	v_mfma_f32_16x16x32_bf16 v[120:123], v[168:171], v[176:179], v[120:123]
	v_mfma_f32_16x16x32_bf16 v[108:111], v[158:161], v[184:187], v[108:111]
	v_mfma_f32_16x16x32_bf16 v[104:107], v[168:171], v[184:187], v[104:107]
	v_mfma_f32_16x16x32_bf16 v[92:95], v[158:161], v[192:195], v[92:95]
	v_mfma_f32_16x16x32_bf16 v[88:91], v[168:171], v[192:195], v[88:91]
	v_mfma_f32_16x16x32_bf16 v[76:79], v[158:161], v[200:203], v[76:79]
	v_mfma_f32_16x16x32_bf16 v[72:75], v[168:171], v[200:203], v[72:75]
	s_setprio 0
	s_barrier
	s_add_i32 s67, s61, s27
	v_add_u32_e32 v153, s62, v149
	v_lshl_add_u64 v[220:221], s[52:53], 0, v[130:131]
	s_mov_b32 m0, s67
	ds_read_b128 v[204:207], v153
	ds_read_b128 v[208:211], v153 offset:1024
	ds_read_b128 v[212:215], v153 offset:2048
	ds_read_b128 v[216:219], v153 offset:3072
	global_load_lds_dwordx4 v[220:221], off
	v_lshl_add_u64 v[222:223], s[52:53], 0, v[134:135]
	s_add_i32 m0, s67, 0x2000
	s_nop 0
	global_load_lds_dwordx4 v[222:223], off
	s_barrier
	s_waitcnt lgkmcnt(0)
	s_setprio 1
	s_waitcnt lgkmcnt(0)
	v_mfma_f32_16x16x32_bf16 v[116:119], v[204:207], v[172:175], v[116:119]
	v_mfma_f32_16x16x32_bf16 v[112:115], v[212:215], v[172:175], v[112:115]
	v_mfma_f32_16x16x32_bf16 v[100:103], v[204:207], v[180:183], v[100:103]
	v_mfma_f32_16x16x32_bf16 v[96:99], v[212:215], v[180:183], v[96:99]
	v_mfma_f32_16x16x32_bf16 v[84:87], v[204:207], v[188:191], v[84:87]
	v_mfma_f32_16x16x32_bf16 v[80:83], v[212:215], v[188:191], v[80:83]
	v_mfma_f32_16x16x32_bf16 v[68:71], v[204:207], v[196:199], v[68:71]
	v_mfma_f32_16x16x32_bf16 v[64:67], v[212:215], v[196:199], v[64:67]
	v_mfma_f32_16x16x32_bf16 v[116:119], v[208:211], v[176:179], v[116:119]
	v_mfma_f32_16x16x32_bf16 v[112:115], v[216:219], v[176:179], v[112:115]
	v_mfma_f32_16x16x32_bf16 v[100:103], v[208:211], v[184:187], v[100:103]
	v_mfma_f32_16x16x32_bf16 v[96:99], v[216:219], v[184:187], v[96:99]
	v_mfma_f32_16x16x32_bf16 v[84:87], v[208:211], v[192:195], v[84:87]
	v_mfma_f32_16x16x32_bf16 v[80:83], v[216:219], v[192:195], v[80:83]
	v_mfma_f32_16x16x32_bf16 v[68:71], v[208:211], v[200:203], v[68:71]
	v_mfma_f32_16x16x32_bf16 v[64:67], v[216:219], v[200:203], v[64:67]
	s_setprio 0
	s_mov_b32 m0, s28
	v_lshl_add_u64 v[224:225], s[54:55], 0, v[128:129]
	s_barrier
	ds_read_b128 v[172:175], v151 offset:16384
	ds_read_b128 v[176:179], v151 offset:17408
	ds_read_b128 v[180:183], v151 offset:18432
	ds_read_b128 v[184:187], v151 offset:19456
	ds_read_b128 v[188:191], v151 offset:20480
	ds_read_b128 v[192:195], v151 offset:21504
	ds_read_b128 v[196:199], v151 offset:22528
	ds_read_b128 v[200:203], v151 offset:23552
	global_load_lds_dwordx4 v[224:225], off
	v_lshl_add_u64 v[226:227], s[54:55], 0, v[132:133]
	s_mov_b32 m0, s29
	s_nop 0
	global_load_lds_dwordx4 v[226:227], off
	s_barrier
; #define PG8_STAGE(bufoff, gbase, voff) do { _Pragma("unroll") for (int _i = 0; _i < 2; ++_i) \
;         __builtin_amdgcn_global_load_lds((const unsigned*)((const char*)(gbase) + (voff)[_i]), (LAS unsigned*)(lds + (bufoff) + ldsw + _i * 8192), 16, 0, 0); } while (0)
; #define PG8_LDA(dst, b, h) do { _Pragma("unroll") for (int m = 0; m < 4; ++m) _Pragma("unroll") for (int k = 0; k < 2; ++k) dst[m][k] = *(const LAS bf16x8*)(lds + PG8_SA(b, h) + aoff + m * 2048 + k * 1024); } while (0)
; #define PG8_LDB(dst, b, h) do { _Pragma("unroll") for (int n = 0; n < 2; ++n) _Pragma("unroll") for (int k = 0; k < 2; ++k) dst[n][k] = *(const LAS bf16x8*)(lds + PG8_SB(b, h) + boff + n * 2048 + k * 1024); } while (0)
; #define PG8_MMA(ai, bj, At, Bt) do { __builtin_amdgcn_s_setprio(1); _Pragma("unroll") for (int m = 0; m < 4; ++m) _Pragma("unroll") for (int n = 0; n < 2; ++n) _Pragma("unroll") for (int k = 0; k < 2; ++k) \
;         acc[ai][bj][m][n] = __builtin_amdgcn_mfma_f32_16x16x32_bf16(Bt[n][k], At[m][k], acc[ai][bj][m][n], 0, 0, 0); __builtin_amdgcn_s_setprio(0); } while (0)
; #define PG8_WAIT_V(n) asm volatile("s_waitcnt vmcnt(" #n ")" ::: "memory")
; #define PG8_WAIT_L(n) asm volatile("s_waitcnt lgkmcnt(" #n ")" ::: "memory")
; #define PG8_BAR __builtin_amdgcn_s_barrier()
; #define PG8_SCHED __builtin_amdgcn_sched_barrier(0)
; template <class Epi, class Sched>
; __device__ __forceinline__ void gemm_phase(LAS unsigned char* lds, const Gemm g, const Sched& S, const Epi& E) {
;     ...
;             PG8_BAR; PG8_WAIT_L(0); PG8_MMA(1, 0, At, B0); PG8_BAR; PG8_SCHED;
;             PG8_STAGE(PG8_SB(0, 1), b2 + hstepB, voffB);
;             PG8_WAIT_V(6); PG8_BAR; PG8_MMA(1, 1, At, B1); PG8_BAR;
;             PG8_LDB(B0, 1, 0); PG8_SCHED; PG8_LDA(At, 1, 0); PG8_STAGE(PG8_SA(0, 1), a2 + hstepA, voffA);
;             PG8_WAIT_L(8); PG8_BAR; PG8_WAIT_L(0); PG8_MMA(0, 0, At, B0); PG8_BAR; PG8_SCHED;
;             PG8_LDB(B1, 1, 1); PG8_STAGE(PG8_SB(1, 0), b3, voffB);
;             PG8_BAR; PG8_WAIT_L(0); PG8_MMA(0, 1, At, B1); PG8_BAR;
	s_waitcnt lgkmcnt(0)
	s_setprio 1
	s_waitcnt lgkmcnt(0)
	v_mfma_f32_16x16x32_bf16 v[60:63], v[154:157], v[172:175], v[60:63]
	v_mfma_f32_16x16x32_bf16 v[56:59], v[162:165], v[172:175], v[56:59]
	v_mfma_f32_16x16x32_bf16 v[44:47], v[154:157], v[180:183], v[44:47]
	v_mfma_f32_16x16x32_bf16 v[40:43], v[162:165], v[180:183], v[40:43]
	v_mfma_f32_16x16x32_bf16 v[28:31], v[154:157], v[188:191], v[28:31]
	v_mfma_f32_16x16x32_bf16 v[24:27], v[162:165], v[188:191], v[24:27]
	v_mfma_f32_16x16x32_bf16 v[12:15], v[154:157], v[196:199], v[12:15]
	v_mfma_f32_16x16x32_bf16 v[8:11], v[162:165], v[196:199], v[8:11]
	v_mfma_f32_16x16x32_bf16 v[60:63], v[158:161], v[176:179], v[60:63]
	v_mfma_f32_16x16x32_bf16 v[56:59], v[168:171], v[176:179], v[56:59]
	v_mfma_f32_16x16x32_bf16 v[44:47], v[158:161], v[184:187], v[44:47]
	v_mfma_f32_16x16x32_bf16 v[40:43], v[168:171], v[184:187], v[40:43]
	v_mfma_f32_16x16x32_bf16 v[28:31], v[158:161], v[192:195], v[28:31]
	v_mfma_f32_16x16x32_bf16 v[24:27], v[168:171], v[192:195], v[24:27]
	v_mfma_f32_16x16x32_bf16 v[12:15], v[158:161], v[200:203], v[12:15]
	v_mfma_f32_16x16x32_bf16 v[8:11], v[168:171], v[200:203], v[8:11]
	s_setprio 0
	s_barrier
	s_add_u32 s68, s52, 0x80000
	s_addc_u32 s69, s53, 0
	s_add_i32 s67, s62, s27
	v_lshl_add_u64 v[154:155], s[68:69], 0, v[130:131]
	s_mov_b32 m0, s67
	s_nop 0
	global_load_lds_dwordx4 v[154:155], off
	v_lshl_add_u64 v[154:155], s[68:69], 0, v[134:135]
	s_add_i32 m0, s67, 0x2000
	s_nop 0
	global_load_lds_dwordx4 v[154:155], off
	global_load_dwordx4 v[228:231], v[232:233], off
	v_lshl_add_u64 v[232:233], v[232:233], 0, s[98:99]
	s_waitcnt vmcnt(7)
	s_barrier
	s_setprio 1
	v_mfma_f32_16x16x32_bf16 v[52:55], v[204:207], v[172:175], v[52:55]
	v_mfma_f32_16x16x32_bf16 v[48:51], v[212:215], v[172:175], v[48:51]
	v_mfma_f32_16x16x32_bf16 v[36:39], v[204:207], v[180:183], v[36:39]
	v_mfma_f32_16x16x32_bf16 v[32:35], v[212:215], v[180:183], v[32:35]
	v_mfma_f32_16x16x32_bf16 v[20:23], v[204:207], v[188:191], v[20:23]
	v_mfma_f32_16x16x32_bf16 v[16:19], v[212:215], v[188:191], v[16:19]
	v_mfma_f32_16x16x32_bf16 v[4:7], v[204:207], v[196:199], v[4:7]
	v_mfma_f32_16x16x32_bf16 v[0:3], v[212:215], v[196:199], v[0:3]
	v_mfma_f32_16x16x32_bf16 v[52:55], v[208:211], v[176:179], v[52:55]
	v_mfma_f32_16x16x32_bf16 v[48:51], v[216:219], v[176:179], v[48:51]
	v_mfma_f32_16x16x32_bf16 v[36:39], v[208:211], v[184:187], v[36:39]
	v_mfma_f32_16x16x32_bf16 v[32:35], v[216:219], v[184:187], v[32:35]
	v_mfma_f32_16x16x32_bf16 v[20:23], v[208:211], v[192:195], v[20:23]
	v_mfma_f32_16x16x32_bf16 v[16:19], v[216:219], v[192:195], v[16:19]
	v_mfma_f32_16x16x32_bf16 v[4:7], v[208:211], v[200:203], v[4:7]
	v_mfma_f32_16x16x32_bf16 v[0:3], v[216:219], v[200:203], v[0:3]
	s_setprio 0
	s_add_i32 s67, 0, 0x18000
	v_add_u32_e32 v153, s67, v149
	s_barrier
	ds_read_b128 v[154:157], v153
	ds_read_b128 v[158:161], v153 offset:1024
	ds_read_b128 v[162:165], v153 offset:2048
	ds_read_b128 v[168:171], v153 offset:3072
	s_add_u32 s54, s54, 0x8000
	s_addc_u32 s55, s55, 0
	s_mov_b32 m0, s33
	v_lshl_add_u64 v[204:205], s[54:55], 0, v[128:129]
	ds_read_b128 v[172:175], v151 offset:32768
	ds_read_b128 v[176:179], v151 offset:33792
	ds_read_b128 v[180:183], v151 offset:34816
	ds_read_b128 v[184:187], v151 offset:35840
	ds_read_b128 v[188:191], v151 offset:36864
	ds_read_b128 v[192:195], v151 offset:37888
	ds_read_b128 v[196:199], v151 offset:38912
	ds_read_b128 v[200:203], v151 offset:39936
	global_load_lds_dwordx4 v[204:205], off
	v_lshl_add_u64 v[204:205], s[54:55], 0, v[132:133]
	s_mov_b32 m0, s56
	s_nop 0
	global_load_lds_dwordx4 v[204:205], off
	s_waitcnt lgkmcnt(8)
	s_barrier
	s_waitcnt lgkmcnt(0)
	s_setprio 1
	s_waitcnt lgkmcnt(0)
	v_mfma_f32_16x16x32_bf16 v[124:127], v[154:157], v[172:175], v[124:127]
	v_mfma_f32_16x16x32_bf16 v[120:123], v[162:165], v[172:175], v[120:123]
	v_mfma_f32_16x16x32_bf16 v[108:111], v[154:157], v[180:183], v[108:111]
	v_mfma_f32_16x16x32_bf16 v[104:107], v[162:165], v[180:183], v[104:107]
	v_mfma_f32_16x16x32_bf16 v[92:95], v[154:157], v[188:191], v[92:95]
	v_mfma_f32_16x16x32_bf16 v[88:91], v[162:165], v[188:191], v[88:91]
	v_mfma_f32_16x16x32_bf16 v[76:79], v[154:157], v[196:199], v[76:79]
	v_mfma_f32_16x16x32_bf16 v[72:75], v[162:165], v[196:199], v[72:75]
	v_mfma_f32_16x16x32_bf16 v[124:127], v[158:161], v[176:179], v[124:127]
	v_mfma_f32_16x16x32_bf16 v[120:123], v[168:171], v[176:179], v[120:123]
	v_mfma_f32_16x16x32_bf16 v[108:111], v[158:161], v[184:187], v[108:111]
	v_mfma_f32_16x16x32_bf16 v[104:107], v[168:171], v[184:187], v[104:107]
	v_mfma_f32_16x16x32_bf16 v[92:95], v[158:161], v[192:195], v[92:95]
	v_mfma_f32_16x16x32_bf16 v[88:91], v[168:171], v[192:195], v[88:91]
	v_mfma_f32_16x16x32_bf16 v[76:79], v[158:161], v[200:203], v[76:79]
	v_mfma_f32_16x16x32_bf16 v[72:75], v[168:171], v[200:203], v[72:75]
	s_setprio 0
	s_barrier
	s_add_i32 s54, 0, 0x1c000
	s_add_i32 s55, s67, s27
	v_add_u32_e32 v153, s54, v149
	v_lshl_add_u64 v[220:221], v[220:221], 0, s[30:31]
	s_mov_b32 m0, s55
	ds_read_b128 v[204:207], v153
	ds_read_b128 v[208:211], v153 offset:1024
	ds_read_b128 v[212:215], v153 offset:2048
	ds_read_b128 v[216:219], v153 offset:3072
	global_load_lds_dwordx4 v[220:221], off
	v_lshl_add_u64 v[220:221], v[222:223], 0, s[30:31]
	s_add_i32 m0, s55, 0x2000
	s_nop 0
	global_load_lds_dwordx4 v[220:221], off
	s_barrier
; #define PG8_STAGE(bufoff, gbase, voff) do { _Pragma("unroll") for (int _i = 0; _i < 2; ++_i) \
;         __builtin_amdgcn_global_load_lds((const unsigned*)((const char*)(gbase) + (voff)[_i]), (LAS unsigned*)(lds + (bufoff) + ldsw + _i * 8192), 16, 0, 0); } while (0)
; #define PG8_LDA(dst, b, h) do { _Pragma("unroll") for (int m = 0; m < 4; ++m) _Pragma("unroll") for (int k = 0; k < 2; ++k) dst[m][k] = *(const LAS bf16x8*)(lds + PG8_SA(b, h) + aoff + m * 2048 + k * 1024); } while (0)
; #define PG8_MMA(ai, bj, At, Bt) do { __builtin_amdgcn_s_setprio(1); _Pragma("unroll") for (int m = 0; m < 4; ++m) _Pragma("unroll") for (int n = 0; n < 2; ++n) _Pragma("unroll") for (int k = 0; k < 2; ++k) \
;         acc[ai][bj][m][n] = __builtin_amdgcn_mfma_f32_16x16x32_bf16(Bt[n][k], At[m][k], acc[ai][bj][m][n], 0, 0, 0); __builtin_amdgcn_s_setprio(0); } while (0)
; #define PG8_WAIT_V(n) asm volatile("s_waitcnt vmcnt(" #n ")" ::: "memory")
; #define PG8_WAIT_L(n) asm volatile("s_waitcnt lgkmcnt(" #n ")" ::: "memory")
; #define PG8_BAR __builtin_amdgcn_s_barrier()
; #define PG8_SCHED __builtin_amdgcn_sched_barrier(0)
; template <class Epi, class Sched>
; __device__ __forceinline__ void gemm_phase(LAS unsigned char* lds, const Gemm g, const Sched& S, const Epi& E) {
;     ...
;             PG8_BAR; PG8_WAIT_L(0); PG8_MMA(0, 1, At, B1); PG8_BAR;
;             PG8_LDA(At, 1, 1); PG8_STAGE(PG8_SA(1, 0), a3, voffA);
;             PG8_BAR; PG8_WAIT_L(0); PG8_MMA(1, 0, At, B0); PG8_BAR; PG8_SCHED;
;             PG8_STAGE(PG8_SB(1, 1), b3 + hstepB, voffB);
;             PG8_WAIT_V(6); PG8_BAR; PG8_MMA(1, 1, At, B1); PG8_BAR;
	s_waitcnt lgkmcnt(0)
	s_setprio 1
	s_waitcnt lgkmcnt(0)
	v_mfma_f32_16x16x32_bf16 v[116:119], v[204:207], v[172:175], v[116:119]
	v_mfma_f32_16x16x32_bf16 v[112:115], v[212:215], v[172:175], v[112:115]
	v_mfma_f32_16x16x32_bf16 v[100:103], v[204:207], v[180:183], v[100:103]
	v_mfma_f32_16x16x32_bf16 v[96:99], v[212:215], v[180:183], v[96:99]
	v_mfma_f32_16x16x32_bf16 v[84:87], v[204:207], v[188:191], v[84:87]
	v_mfma_f32_16x16x32_bf16 v[80:83], v[212:215], v[188:191], v[80:83]
	v_mfma_f32_16x16x32_bf16 v[68:71], v[204:207], v[196:199], v[68:71]
	v_mfma_f32_16x16x32_bf16 v[64:67], v[212:215], v[196:199], v[64:67]
	v_mfma_f32_16x16x32_bf16 v[116:119], v[208:211], v[176:179], v[116:119]
	v_mfma_f32_16x16x32_bf16 v[112:115], v[216:219], v[176:179], v[112:115]
	v_mfma_f32_16x16x32_bf16 v[100:103], v[208:211], v[184:187], v[100:103]
	v_mfma_f32_16x16x32_bf16 v[96:99], v[216:219], v[184:187], v[96:99]
	v_mfma_f32_16x16x32_bf16 v[84:87], v[208:211], v[192:195], v[84:87]
	v_mfma_f32_16x16x32_bf16 v[80:83], v[216:219], v[192:195], v[80:83]
	v_mfma_f32_16x16x32_bf16 v[68:71], v[208:211], v[200:203], v[68:71]
	v_mfma_f32_16x16x32_bf16 v[64:67], v[216:219], v[200:203], v[64:67]
	s_setprio 0
	s_mov_b32 m0, s58
	v_lshl_add_u64 v[220:221], v[224:225], 0, s[30:31]
	s_barrier
	ds_read_b128 v[172:175], v151 offset:49152
	ds_read_b128 v[176:179], v151 offset:50176
	ds_read_b128 v[180:183], v151 offset:51200
	ds_read_b128 v[184:187], v151 offset:52224
	ds_read_b128 v[188:191], v151 offset:53248
	ds_read_b128 v[192:195], v151 offset:54272
	ds_read_b128 v[196:199], v151 offset:55296
	ds_read_b128 v[200:203], v151 offset:56320
	global_load_lds_dwordx4 v[220:221], off
	v_lshl_add_u64 v[220:221], v[226:227], 0, s[30:31]
	s_mov_b32 m0, s59
	s_nop 0
	global_load_lds_dwordx4 v[220:221], off
	s_barrier
	s_waitcnt lgkmcnt(0)
	s_setprio 1
	s_waitcnt lgkmcnt(0)
	v_mfma_f32_16x16x32_bf16 v[60:63], v[154:157], v[172:175], v[60:63]
	v_mfma_f32_16x16x32_bf16 v[56:59], v[162:165], v[172:175], v[56:59]
	v_mfma_f32_16x16x32_bf16 v[44:47], v[154:157], v[180:183], v[44:47]
	v_mfma_f32_16x16x32_bf16 v[40:43], v[162:165], v[180:183], v[40:43]
	v_mfma_f32_16x16x32_bf16 v[28:31], v[154:157], v[188:191], v[28:31]
	v_mfma_f32_16x16x32_bf16 v[24:27], v[162:165], v[188:191], v[24:27]
	v_mfma_f32_16x16x32_bf16 v[12:15], v[154:157], v[196:199], v[12:15]
	v_mfma_f32_16x16x32_bf16 v[8:11], v[162:165], v[196:199], v[8:11]
	v_mfma_f32_16x16x32_bf16 v[60:63], v[158:161], v[176:179], v[60:63]
	v_mfma_f32_16x16x32_bf16 v[56:59], v[168:171], v[176:179], v[56:59]
	v_mfma_f32_16x16x32_bf16 v[44:47], v[158:161], v[184:187], v[44:47]
	v_mfma_f32_16x16x32_bf16 v[40:43], v[168:171], v[184:187], v[40:43]
	v_mfma_f32_16x16x32_bf16 v[28:31], v[158:161], v[192:195], v[28:31]
	v_mfma_f32_16x16x32_bf16 v[24:27], v[168:171], v[192:195], v[24:27]
	v_mfma_f32_16x16x32_bf16 v[12:15], v[158:161], v[200:203], v[12:15]
	v_mfma_f32_16x16x32_bf16 v[8:11], v[168:171], v[200:203], v[8:11]
	s_setprio 0
	s_barrier
	s_add_u32 s52, s52, 0x80080
	s_addc_u32 s53, s53, 0
	s_add_i32 s54, s54, s27
	v_lshl_add_u64 v[154:155], s[52:53], 0, v[130:131]
	s_mov_b32 m0, s54
	s_nop 0
	global_load_lds_dwordx4 v[154:155], off
	v_lshl_add_u64 v[154:155], s[52:53], 0, v[134:135]
	s_add_i32 m0, s54, 0x2000
	s_nop 0
	global_load_lds_dwordx4 v[154:155], off
	global_load_dwordx4 v[228:231], v[232:233], off
	v_lshl_add_u64 v[232:233], v[232:233], 0, s[98:99]
	s_waitcnt vmcnt(7)
	s_barrier
; #define PG8_MMA(ai, bj, At, Bt) do { __builtin_amdgcn_s_setprio(1); _Pragma("unroll") for (int m = 0; m < 4; ++m) _Pragma("unroll") for (int n = 0; n < 2; ++n) _Pragma("unroll") for (int k = 0; k < 2; ++k) \
;         acc[ai][bj][m][n] = __builtin_amdgcn_mfma_f32_16x16x32_bf16(Bt[n][k], At[m][k], acc[ai][bj][m][n], 0, 0, 0); __builtin_amdgcn_s_setprio(0); } while (0)
; #define PG8_WAIT_V(n) asm volatile("s_waitcnt vmcnt(" #n ")" ::: "memory")
; #define PG8_BAR __builtin_amdgcn_s_barrier()
; template <class Epi, class Sched>
; __device__ __forceinline__ void gemm_phase(LAS unsigned char* lds, const Gemm g, const Sched& S, const Epi& E) {
;     ...
;             PG8_WAIT_V(6); PG8_BAR; PG8_MMA(1, 1, At, B1); PG8_BAR;
;         }
;         if constexpr (!Epi::AFTER_DRAIN) E(acc, cur, wr, wc, fr, fq);
;         if (!has_next) break;
; #pragma unroll
;         for (int a = 0; a < 2; ++a)
; #pragma unroll
;             for (int b = 0; b < 2; ++b)
; #pragma unroll
;                 for (int m = 0; m < 4; ++m)
; #pragma unroll
;                     for (int n = 0; n < 2; ++n) acc[a][b][m][n] = (f32x4){0.f, 0.f, 0.f, 0.f};
;         cur = nxt; cA = nA; cB = nB; ++ui;
	s_setprio 1
	v_mfma_f32_16x16x32_bf16 v[52:55], v[204:207], v[172:175], v[52:55]
	v_mfma_f32_16x16x32_bf16 v[48:51], v[212:215], v[172:175], v[48:51]
	v_mfma_f32_16x16x32_bf16 v[36:39], v[204:207], v[180:183], v[36:39]
	v_mfma_f32_16x16x32_bf16 v[32:35], v[212:215], v[180:183], v[32:35]
	v_mfma_f32_16x16x32_bf16 v[20:23], v[204:207], v[188:191], v[20:23]
	v_mfma_f32_16x16x32_bf16 v[16:19], v[212:215], v[188:191], v[16:19]
	v_mfma_f32_16x16x32_bf16 v[4:7], v[204:207], v[196:199], v[4:7]
	v_mfma_f32_16x16x32_bf16 v[0:3], v[212:215], v[196:199], v[0:3]
	v_mfma_f32_16x16x32_bf16 v[52:55], v[208:211], v[176:179], v[52:55]
	v_mfma_f32_16x16x32_bf16 v[48:51], v[216:219], v[176:179], v[48:51]
	v_mfma_f32_16x16x32_bf16 v[36:39], v[208:211], v[184:187], v[36:39]
	v_mfma_f32_16x16x32_bf16 v[32:35], v[216:219], v[184:187], v[32:35]
	v_mfma_f32_16x16x32_bf16 v[20:23], v[208:211], v[192:195], v[20:23]
	v_mfma_f32_16x16x32_bf16 v[16:19], v[216:219], v[192:195], v[16:19]
	v_mfma_f32_16x16x32_bf16 v[4:7], v[208:211], v[200:203], v[4:7]
	v_mfma_f32_16x16x32_bf16 v[0:3], v[216:219], v[200:203], v[0:3]
	s_setprio 0
	s_add_i32 s66, s66, 2
	s_add_u32 s64, s64, 0x100
	s_addc_u32 s65, s65, 0
	s_add_u32 s50, s50, 0x400000
	s_addc_u32 s51, s51, 0
	v_lshl_add_u64 v[146:147], v[146:147], 0, s[38:39]
	s_cmp_gt_u32 s66, 29
	v_lshl_add_u64 v[144:145], v[144:145], 0, s[38:39]
	s_barrier
	s_cbranch_scc0 .LBB0_430
	s_andn2_b64 vcc, exec, s[4:5]
	s_cbranch_vccnz .LBB0_422
	v_mov_b32_e32 v0, 0
	s_mov_b32 s16, s40
	s_mov_b32 s14, s42
	s_mov_b64 s[18:19], s[48:49]
	s_mov_b64 s[20:21], s[46:47]
	s_mov_b32 s60, s44
	v_mov_b32_e32 v1, v0
	v_mov_b32_e32 v2, v0
	v_mov_b32_e32 v3, v0
	v_mov_b32_e32 v4, v0
	v_mov_b32_e32 v5, v0
	v_mov_b32_e32 v6, v0
	v_mov_b32_e32 v7, v0
	v_mov_b32_e32 v16, v0
	v_mov_b32_e32 v17, v0
	v_mov_b32_e32 v18, v0
	v_mov_b32_e32 v19, v0
	v_mov_b32_e32 v20, v0
	v_mov_b32_e32 v21, v0
	v_mov_b32_e32 v22, v0
	v_mov_b32_e32 v23, v0
	v_mov_b32_e32 v32, v0
	v_mov_b32_e32 v33, v0
	v_mov_b32_e32 v34, v0
	v_mov_b32_e32 v35, v0
	v_mov_b32_e32 v36, v0
	v_mov_b32_e32 v37, v0
	v_mov_b32_e32 v38, v0
	v_mov_b32_e32 v39, v0
	v_mov_b32_e32 v48, v0
	v_mov_b32_e32 v49, v0
	v_mov_b32_e32 v50, v0
	v_mov_b32_e32 v51, v0
	v_mov_b32_e32 v52, v0
	v_mov_b32_e32 v53, v0
	v_mov_b32_e32 v54, v0
	v_mov_b32_e32 v55, v0
	v_mov_b32_e32 v8, v0
	v_mov_b32_e32 v9, v0
	v_mov_b32_e32 v10, v0
	v_mov_b32_e32 v11, v0
	v_mov_b32_e32 v12, v0
	v_mov_b32_e32 v13, v0
	v_mov_b32_e32 v14, v0
	v_mov_b32_e32 v15, v0
	v_mov_b32_e32 v24, v0
	v_mov_b32_e32 v25, v0
	v_mov_b32_e32 v26, v0
	v_mov_b32_e32 v27, v0
	v_mov_b32_e32 v28, v0
	v_mov_b32_e32 v29, v0
	v_mov_b32_e32 v30, v0
	v_mov_b32_e32 v31, v0
	v_mov_b32_e32 v40, v0
	v_mov_b32_e32 v41, v0
	v_mov_b32_e32 v42, v0
	v_mov_b32_e32 v43, v0
	v_mov_b32_e32 v44, v0
	v_mov_b32_e32 v45, v0
	v_mov_b32_e32 v46, v0
	v_mov_b32_e32 v47, v0
	v_mov_b32_e32 v56, v0
	v_mov_b32_e32 v57, v0
	v_mov_b32_e32 v58, v0
	v_mov_b32_e32 v59, v0
	v_mov_b32_e32 v60, v0
	v_mov_b32_e32 v61, v0
	v_mov_b32_e32 v62, v0
	v_mov_b32_e32 v63, v0
	v_mov_b32_e32 v64, v0
	v_mov_b32_e32 v65, v0
	v_mov_b32_e32 v66, v0
	v_mov_b32_e32 v67, v0
	v_mov_b32_e32 v68, v0
	v_mov_b32_e32 v69, v0
	v_mov_b32_e32 v70, v0
	v_mov_b32_e32 v71, v0
	v_mov_b32_e32 v80, v0
	v_mov_b32_e32 v81, v0
	v_mov_b32_e32 v82, v0
	v_mov_b32_e32 v83, v0
	v_mov_b32_e32 v84, v0
	v_mov_b32_e32 v85, v0
	v_mov_b32_e32 v86, v0
	v_mov_b32_e32 v87, v0
	v_mov_b32_e32 v96, v0
	v_mov_b32_e32 v97, v0
	v_mov_b32_e32 v98, v0
	v_mov_b32_e32 v99, v0
	v_mov_b32_e32 v100, v0
	v_mov_b32_e32 v101, v0
	v_mov_b32_e32 v102, v0
	v_mov_b32_e32 v103, v0
	v_mov_b32_e32 v112, v0
	v_mov_b32_e32 v113, v0
	v_mov_b32_e32 v114, v0
	v_mov_b32_e32 v115, v0
	v_mov_b32_e32 v116, v0
	v_mov_b32_e32 v117, v0
	v_mov_b32_e32 v118, v0
	v_mov_b32_e32 v119, v0
	v_mov_b32_e32 v72, v0
	v_mov_b32_e32 v73, v0
	v_mov_b32_e32 v74, v0
	v_mov_b32_e32 v75, v0
	v_mov_b32_e32 v76, v0
	v_mov_b32_e32 v77, v0
	v_mov_b32_e32 v78, v0
	v_mov_b32_e32 v79, v0
	v_mov_b32_e32 v88, v0
	v_mov_b32_e32 v89, v0
	v_mov_b32_e32 v90, v0
	v_mov_b32_e32 v91, v0
	v_mov_b32_e32 v92, v0
	v_mov_b32_e32 v93, v0
	v_mov_b32_e32 v94, v0
	v_mov_b32_e32 v95, v0
	v_mov_b32_e32 v104, v0
	v_mov_b32_e32 v105, v0
	v_mov_b32_e32 v106, v0
	v_mov_b32_e32 v107, v0
	v_mov_b32_e32 v108, v0
	v_mov_b32_e32 v109, v0
	v_mov_b32_e32 v110, v0
	v_mov_b32_e32 v111, v0
	v_mov_b32_e32 v120, v0
	v_mov_b32_e32 v121, v0
	v_mov_b32_e32 v122, v0
	v_mov_b32_e32 v123, v0
	v_mov_b32_e32 v124, v0
	v_mov_b32_e32 v125, v0
	v_mov_b32_e32 v126, v0
	v_mov_b32_e32 v127, v0
	s_branch .LBB0_422
